# P3: wave 0 issues its conv tap loads right behind its gate loads so the gate arithmetic covers their latency
# baseline (speedup 1.0000x reference)
.LBB0_285:
	s_lshr_b32 s0, s97, 8
	s_add_i32 s84, s97, s58
	s_xor_b32 s0, s0, s97
	s_bitcmp0_b32 s0, 0
	s_cselect_b64 s[64:65], -1, 0
	s_and_b64 s[0:1], s[64:65], exec
	s_cselect_b32 s6, s84, s97
	v_mov_b32_e32 v77, v20
	s_bfe_u32 s3, s6, 0x60003
	s_nop 0
	v_cmp_lt_u32_e32 vcc, 63, v77
	s_and_saveexec_b64 s[0:1], vcc
	s_xor_b64 s[0:1], exec, s[0:1]
	s_lshl_b32 s7, s3, 6
	s_or_saveexec_b64 s[4:5], s[0:1]
	s_ashr_i32 s66, s6, 9
	s_bfe_u32 s14, s6, 0x20001
	v_mov_b32_e32 v0, s7
	s_xor_b64 exec, exec, s[4:5]
	s_cbranch_execz .LBB0_289
	s_ashr_i32 s67, s66, 31
	s_lshl_b64 s[0:1], s[66:67], 12
	s_lshl_b32 s6, s3, 6
	s_or_b32 s0, s0, s6
	v_or_b32_e32 v0, s0, v77
	v_mov_b32_e32 v1, s1
	v_lshlrev_b64 v[0:1], 5, v[0:1]
	v_lshl_add_u64 v[0:1], s[34:35], 0, v[0:1]
	s_lshl_b32 s38, s14, 2
	v_lshl_add_u64 v[0:1], v[0:1], 0, s[38:39]
	global_load_dword v2, v[0:1], off
	v_mov_b32_e32 v3, s38
	global_load_dword v4, v3, s[16:17]
	s_nop 0
	global_load_dword v3, v3, s[50:51]
	s_nop 0
	global_load_dword v5, v[0:1], off offset:16
	v_lshlrev_b32_e32 v90, 4, v77
	v_and_b32_e32 v90, 0x70, v90
	v_lshlrev_b32_e32 v90, 1, v90
	v_lshl_or_b32 v90, s14, 8, v90
	v_mov_b32_e32 v91, 0
	v_lshl_add_u64 v[90:91], s[22:23], 0, v[90:91]
	v_lshl_add_u64 v[90:91], v[90:91], 0, s[40:41]
	v_ashrrev_i32_e32 v92, 3, v77
	v_add_u32_e32 v92, s6, v92
	v_mov_b32_e32 v93, s66
	v_lshlrev_b32_e32 v93, 12, v93
	v_mov_b32_e32 v89, 0
	v_add_u32_e32 v88, -3, v92
	v_max_i32_e32 v88, 0, v88
	v_add_u32_e32 v88, v93, v88
	v_lshlrev_b64 v[80:81], 13, v[88:89]
	v_lshl_add_u64 v[80:81], v[90:91], 0, v[80:81]
	v_add_u32_e32 v88, -2, v92
	v_max_i32_e32 v88, 0, v88
	v_add_u32_e32 v88, v93, v88
	v_lshlrev_b64 v[82:83], 13, v[88:89]
	v_lshl_add_u64 v[82:83], v[90:91], 0, v[82:83]
	v_add_u32_e32 v88, -1, v92
	v_max_i32_e32 v88, 0, v88
	v_add_u32_e32 v88, v93, v88
	v_lshlrev_b64 v[84:85], 13, v[88:89]
	v_lshl_add_u64 v[84:85], v[90:91], 0, v[84:85]
	v_add_u32_e32 v88, v93, v92
	v_lshlrev_b64 v[86:87], 13, v[88:89]
	v_lshl_add_u64 v[86:87], v[90:91], 0, v[86:87]
	global_load_dwordx4 v[144:147], v[80:81], off
	global_load_dwordx4 v[148:151], v[80:81], off offset:16
	global_load_dwordx4 v[152:155], v[82:83], off
	global_load_dwordx4 v[156:159], v[82:83], off offset:16
	global_load_dwordx4 v[160:163], v[84:85], off
	global_load_dwordx4 v[164:167], v[84:85], off offset:16
	global_load_dwordx4 v[168:171], v[86:87], off
	global_load_dwordx4 v[172:175], v[86:87], off offset:16
	global_load_dwordx4 v[176:179], v[80:81], off offset:1024
	global_load_dwordx4 v[180:183], v[80:81], off offset:1040
	global_load_dwordx4 v[184:187], v[82:83], off offset:1024
	global_load_dwordx4 v[188:191], v[82:83], off offset:1040
	global_load_dwordx4 v[192:195], v[84:85], off offset:1024
	global_load_dwordx4 v[196:199], v[84:85], off offset:1040
	global_load_dwordx4 v[200:203], v[86:87], off offset:1024
	global_load_dwordx4 v[204:207], v[86:87], off offset:1040
	global_load_dwordx4 v[208:211], v[80:81], off offset:2048
	global_load_dwordx4 v[212:215], v[80:81], off offset:2064
	global_load_dwordx4 v[216:219], v[82:83], off offset:2048
	global_load_dwordx4 v[220:223], v[82:83], off offset:2064
	global_load_dwordx4 v[224:227], v[84:85], off offset:2048
	global_load_dwordx4 v[228:231], v[84:85], off offset:2064
	global_load_dwordx4 v[232:235], v[86:87], off offset:2048
	global_load_dwordx4 v[236:239], v[86:87], off offset:2064
	s_waitcnt vmcnt(26)
	v_add_f32_e32 v0, v2, v4
	v_mul_f32_e64 v1, |v0|, s72
	v_exp_f32_e32 v2, v1
	s_waitcnt vmcnt(25)
	v_mul_f32_e32 v1, 0x3fb8aa3b, v3
	v_exp_f32_e32 v3, v1
	v_max_f32_e32 v4, 0, v0
	v_add_f32_e32 v6, 1.0, v2
	v_add_f32_e32 v7, -1.0, v6
	v_frexp_mant_f32_e32 v8, v6
	v_cvt_f64_f32_e32 v[0:1], v6
	v_sub_f32_e32 v9, v7, v6
	v_frexp_exp_i32_f64_e32 v0, v[0:1]
	v_cmp_gt_f32_e32 vcc, s73, v8
	v_sub_f32_e32 v7, v2, v7
	v_add_f32_e32 v1, 1.0, v9
	v_subbrev_co_u32_e32 v0, vcc, 0, v0, vcc
	v_add_f32_e32 v1, v7, v1
	v_sub_u32_e32 v7, 0, v0
	v_cvt_f32_i32_e32 v0, v0
	v_ldexp_f32 v6, v6, v7
	v_ldexp_f32 v1, v1, v7
	v_add_f32_e32 v7, -1.0, v6
	v_add_f32_e32 v8, 1.0, v6
	v_add_f32_e32 v9, 1.0, v7
	v_add_f32_e32 v10, -1.0, v8
	v_sub_f32_e32 v9, v6, v9
	v_sub_f32_e32 v6, v6, v10
	v_mul_f32_e32 v10, 0x3f317218, v0
	v_add_f32_e32 v9, v1, v9
	v_add_f32_e32 v1, v1, v6
	v_fma_f32 v6, v0, s74, -v10
	v_add_f32_e32 v11, v7, v9
	v_add_f32_e32 v12, v8, v1
	v_fmac_f32_e32 v6, 0xb102e308, v0
	v_sub_f32_e32 v0, v11, v7
	v_sub_f32_e32 v7, v12, v8
	v_rcp_f32_e32 v8, v12
	v_add_f32_e32 v13, v10, v6
	v_sub_f32_e32 v1, v1, v7
	v_sub_f32_e32 v7, v13, v10
	v_sub_f32_e32 v6, v6, v7
	v_mul_f32_e32 v7, v11, v8
	v_sub_f32_e32 v0, v9, v0
	v_mul_f32_e32 v9, v12, v7
	v_fma_f32 v10, v7, v12, -v9
	v_fmac_f32_e32 v10, v7, v1
	v_add_f32_e32 v14, v9, v10
	v_sub_f32_e32 v15, v11, v14
	v_sub_f32_e32 v9, v14, v9
	v_sub_f32_e32 v11, v11, v15
	v_sub_f32_e32 v9, v9, v10
	v_sub_f32_e32 v10, v11, v14
	v_add_f32_e32 v0, v0, v10
	v_add_f32_e32 v0, v9, v0
	v_add_f32_e32 v9, v15, v0
	v_mul_f32_e32 v10, v8, v9
	v_sub_f32_e32 v11, v15, v9
	v_mul_f32_e32 v14, v12, v10
	v_add_f32_e32 v0, v0, v11
	v_add_f32_e32 v11, v7, v10
	v_fma_f32 v12, v10, v12, -v14
	v_sub_f32_e32 v7, v11, v7
	v_fmac_f32_e32 v12, v10, v1
	v_sub_f32_e32 v1, v10, v7
	v_add_f32_e32 v7, v14, v12
	v_sub_f32_e32 v10, v7, v14
	v_sub_f32_e32 v14, v9, v7
	v_sub_f32_e32 v9, v9, v14
	v_sub_f32_e32 v7, v9, v7
	v_sub_f32_e32 v10, v10, v12
	v_add_f32_e32 v0, v0, v7
	v_add_f32_e32 v0, v10, v0
	v_add_f32_e32 v0, v14, v0
	v_mul_f32_e32 v0, v8, v0
	v_add_f32_e32 v0, v1, v0
	v_add_f32_e32 v1, v11, v0
	v_mul_f32_e32 v7, v1, v1
	v_fmamk_f32 v10, v7, 0x3e9b6dac, v60
	v_sub_f32_e32 v8, v1, v11
	v_ldexp_f32 v9, v1, 1
	v_mul_f32_e32 v1, v1, v7
	v_fmaak_f32 v7, v7, v10, 0x3f2aaada
	v_mul_f32_e32 v1, v1, v7
	v_add_f32_e32 v7, v9, v1
	v_sub_f32_e32 v0, v0, v8
	v_sub_f32_e32 v8, v7, v9
	v_ldexp_f32 v0, v0, 1
	v_sub_f32_e32 v1, v1, v8
	v_add_f32_e32 v0, v0, v1
	v_add_f32_e32 v1, v7, v0
	v_sub_f32_e32 v7, v1, v7
	v_add_f32_e32 v8, v13, v1
	v_sub_f32_e32 v0, v0, v7
	v_sub_f32_e32 v7, v8, v13
	v_sub_f32_e32 v9, v8, v7
	v_sub_f32_e32 v1, v1, v7
	v_add_f32_e32 v7, v6, v0
	v_sub_f32_e32 v9, v13, v9
	v_sub_f32_e32 v10, v7, v6
	v_add_f32_e32 v1, v1, v9
	v_sub_f32_e32 v9, v7, v10
	v_sub_f32_e32 v0, v0, v10
	v_sub_f32_e32 v6, v6, v9
	v_add_f32_e32 v1, v7, v1
	v_add_f32_e32 v0, v0, v6
	v_add_f32_e32 v6, v8, v1
	v_sub_f32_e32 v7, v6, v8
	v_sub_f32_e32 v1, v1, v7
	v_add_f32_e32 v0, v0, v1
	v_add_f32_e32 v0, v6, v0
	v_cmp_neq_f32_e32 vcc, s75, v2
	s_nop 1
	v_cndmask_b32_e32 v0, v62, v0, vcc
	v_cmp_ngt_f32_e32 vcc, -1.0, v2
	s_nop 1
	v_cndmask_b32_e32 v0, v63, v0, vcc
	v_cmp_neq_f32_e32 vcc, -1.0, v2
	s_nop 1
	v_cndmask_b32_e32 v0, v64, v0, vcc
	v_cmp_lt_f32_e64 vcc, |v2|, s76
	s_nop 1
	v_cndmask_b32_e32 v0, v0, v2, vcc
	v_add_f32_e32 v0, v4, v0
	v_mul_f32_e64 v1, v0, -v3
	ds_bpermute_b32 v2, v21, v1
	v_cmp_eq_u32_e32 vcc, 0, v77
	s_waitcnt lgkmcnt(0)
	v_fma_f32 v0, v0, -v3, v2
	v_cndmask_b32_e32 v0, v0, v1, vcc
	ds_bpermute_b32 v1, v52, v0
	v_cmp_gt_u32_e32 vcc, 2, v77
	s_waitcnt vmcnt(24)
	v_mul_f32_e32 v3, 0xbfb8aa3b, v5
	v_exp_f32_e32 v3, v3
	v_lshl_add_u32 v2, v77, 2, 0
	s_waitcnt lgkmcnt(0)
	v_add_f32_e32 v1, v0, v1
	v_cndmask_b32_e32 v0, v1, v0, vcc
	ds_bpermute_b32 v1, v53, v0
	v_cmp_gt_u32_e32 vcc, 4, v77
	v_add_f32_e32 v3, 1.0, v3
	v_div_scale_f32 v6, s[0:1], v3, v3, 1.0
	s_waitcnt lgkmcnt(0)
	v_add_f32_e32 v1, v0, v1
	v_cndmask_b32_e32 v0, v1, v0, vcc
	ds_bpermute_b32 v1, v54, v0
	v_cmp_gt_u32_e64 s[0:1], 8, v77
	v_rcp_f32_e32 v8, v6
	v_div_scale_f32 v7, vcc, 1.0, v3, 1.0
	s_waitcnt lgkmcnt(0)
	v_add_f32_e32 v1, v0, v1
	v_cndmask_b32_e64 v0, v1, v0, s[0:1]
	ds_bpermute_b32 v1, v55, v0
	v_cmp_gt_u32_e64 s[0:1], 16, v77
	v_fma_f32 v9, -v6, v8, 1.0
	v_fmac_f32_e32 v8, v9, v8
	v_mul_f32_e32 v9, v7, v8
	s_waitcnt lgkmcnt(0)
	v_add_f32_e32 v1, v0, v1
	v_cndmask_b32_e64 v0, v1, v0, s[0:1]
	ds_bpermute_b32 v1, v56, v0
	v_fma_f32 v10, -v6, v9, v7
	v_fmac_f32_e32 v9, v10, v8
	v_fma_f32 v6, -v6, v9, v7
	v_div_fmas_f32 v6, v6, v8, v9
	s_waitcnt lgkmcnt(0)
	v_add_f32_e32 v1, v0, v1
	v_cmp_gt_u32_e32 vcc, 32, v77
	v_add_u32_e32 v5, 0x11100, v2
	v_div_fixup_f32 v3, v6, v3, 1.0
	v_cndmask_b32_e32 v0, v1, v0, vcc
	v_mul_f32_e32 v1, 0x3fb8aa3b, v0
	v_exp_f32_e32 v1, v1
	v_add_u32_e32 v4, 0x11000, v2
	v_add_u32_e32 v2, 0x11200, v2
	ds_write_b32 v5, v3
	ds_write_b32 v4, v0
	v_mul_f32_e32 v0, v3, v1
	ds_write_b32 v2, v0
	v_mov_b32_e32 v0, s6
.LBB0_289:
	s_or_b64 exec, exec, s[4:5]
	v_lshlrev_b32_e32 v1, 4, v77
	v_and_b32_e32 v24, 0x70, v1
	v_lshlrev_b32_e32 v4, 1, v24
	v_ashrrev_i32_e32 v78, 3, v77
	v_lshl_or_b32 v22, s14, 8, v4
	v_add_u32_e32 v25, v0, v78
	s_lshl_b32 s12, s66, 12
	v_lshl_add_u64 v[32:33], s[22:23], 0, v[22:23]
	v_mov_b32_e32 v22, v23
	v_lshl_add_u32 v5, v24, 2, s77
	v_lshl_add_u64 v[34:35], v[32:33], 0, s[40:41]
	v_cmp_lt_i32_e64 s[0:1], 2, v25
	v_add3_u32 v0, v25, s12, -3
	v_mov_b64_e32 v[26:27], v[22:23]
	v_mov_b64_e32 v[18:19], v[22:23]
	v_mov_b64_e32 v[14:15], v[22:23]
	v_mov_b64_e32 v[10:11], v[22:23]
	v_mov_b64_e32 v[16:17], v[22:23]
	v_mov_b64_e32 v[12:13], v[22:23]
	v_mov_b64_e32 v[8:9], v[22:23]
	v_mov_b64_e32 v[6:7], v[22:23]
	s_cmp_eq_u32 s85, 0
	s_cbranch_scc1 .Lcv_skip_hoist
	v_mov_b32_e32 v89, 0
	v_add_u32_e32 v88, -3, v25
	v_max_i32_e32 v88, 0, v88
	v_add_u32_e32 v88, s12, v88
	v_lshlrev_b64 v[80:81], 13, v[88:89]
	v_lshl_add_u64 v[80:81], v[34:35], 0, v[80:81]
	v_add_u32_e32 v88, -2, v25
	v_max_i32_e32 v88, 0, v88
	v_add_u32_e32 v88, s12, v88
	v_lshlrev_b64 v[82:83], 13, v[88:89]
	v_lshl_add_u64 v[82:83], v[34:35], 0, v[82:83]
	v_add_u32_e32 v88, -1, v25
	v_max_i32_e32 v88, 0, v88
	v_add_u32_e32 v88, s12, v88
	v_lshlrev_b64 v[84:85], 13, v[88:89]
	v_lshl_add_u64 v[84:85], v[34:35], 0, v[84:85]
	v_add_u32_e32 v88, s12, v25
	v_lshlrev_b64 v[86:87], 13, v[88:89]
	v_lshl_add_u64 v[86:87], v[34:35], 0, v[86:87]
	global_load_dwordx4 v[144:147], v[80:81], off
	global_load_dwordx4 v[148:151], v[80:81], off offset:16
	global_load_dwordx4 v[152:155], v[82:83], off
	global_load_dwordx4 v[156:159], v[82:83], off offset:16
	global_load_dwordx4 v[160:163], v[84:85], off
	global_load_dwordx4 v[164:167], v[84:85], off offset:16
	global_load_dwordx4 v[168:171], v[86:87], off
	global_load_dwordx4 v[172:175], v[86:87], off offset:16
	global_load_dwordx4 v[176:179], v[80:81], off offset:1024
	global_load_dwordx4 v[180:183], v[80:81], off offset:1040
	global_load_dwordx4 v[184:187], v[82:83], off offset:1024
	global_load_dwordx4 v[188:191], v[82:83], off offset:1040
	global_load_dwordx4 v[192:195], v[84:85], off offset:1024
	global_load_dwordx4 v[196:199], v[84:85], off offset:1040
	global_load_dwordx4 v[200:203], v[86:87], off offset:1024
	global_load_dwordx4 v[204:207], v[86:87], off offset:1040
	global_load_dwordx4 v[208:211], v[80:81], off offset:2048
	global_load_dwordx4 v[212:215], v[80:81], off offset:2064
	global_load_dwordx4 v[216:219], v[82:83], off offset:2048
	global_load_dwordx4 v[220:223], v[82:83], off offset:2064
	global_load_dwordx4 v[224:227], v[84:85], off offset:2048
	global_load_dwordx4 v[228:231], v[84:85], off offset:2064
	global_load_dwordx4 v[232:235], v[86:87], off offset:2048
	global_load_dwordx4 v[236:239], v[86:87], off offset:2064
.Lcv_skip_hoist:
	s_and_saveexec_b64 s[4:5], s[0:1]
	s_cbranch_execz .LBB0_291
	v_ashrrev_i32_e32 v1, 31, v0
	v_lshlrev_b64 v[2:3], 13, v[0:1]
	v_lshl_add_u64 v[2:3], v[34:35], 0, v[2:3]
	s_waitcnt vmcnt(22)
	v_mov_b32_e32 v6, v144
	v_mov_b32_e32 v7, v145
	v_mov_b32_e32 v8, v146
	v_mov_b32_e32 v9, v147
	v_mov_b32_e32 v10, v148
	v_mov_b32_e32 v11, v149
	v_mov_b32_e32 v12, v150
	v_mov_b32_e32 v13, v151
	ds_read_b128 v[14:17], v5
	ds_read_b128 v[26:29], v5 offset:16
	ds_read_b128 v[36:39], v5 offset:32
	ds_read_b128 v[40:43], v5 offset:48
	s_nop 0
	v_lshlrev_b32_e32 v2, 16, v6
	v_and_b32_e32 v3, 0xffff0000, v6
	v_lshlrev_b32_e32 v6, 16, v7
	v_and_b32_e32 v7, 0xffff0000, v7
	v_lshlrev_b32_e32 v18, 16, v8
	v_and_b32_e32 v19, 0xffff0000, v8
	v_lshlrev_b32_e32 v8, 16, v9
	v_and_b32_e32 v9, 0xffff0000, v9
	s_nop 0
	v_lshlrev_b32_e32 v30, 16, v10
	v_and_b32_e32 v31, 0xffff0000, v10
	v_lshlrev_b32_e32 v44, 16, v11
	v_and_b32_e32 v45, 0xffff0000, v11
	v_lshlrev_b32_e32 v46, 16, v12
	v_and_b32_e32 v47, 0xffff0000, v12
	v_lshlrev_b32_e32 v48, 16, v13
	v_and_b32_e32 v49, 0xffff0000, v13
	s_waitcnt lgkmcnt(3)
	v_pk_fma_f32 v[10:11], v[14:15], v[2:3], 0 op_sel_hi:[1,1,0]
	v_pk_fma_f32 v[14:15], v[16:17], v[6:7], 0 op_sel_hi:[1,1,0]
	s_waitcnt lgkmcnt(2)
	v_pk_fma_f32 v[6:7], v[26:27], v[18:19], 0 op_sel_hi:[1,1,0]
	v_pk_fma_f32 v[8:9], v[28:29], v[8:9], 0 op_sel_hi:[1,1,0]
	s_waitcnt lgkmcnt(1)
	v_pk_fma_f32 v[18:19], v[36:37], v[30:31], 0 op_sel_hi:[1,1,0]
	v_pk_fma_f32 v[26:27], v[38:39], v[44:45], 0 op_sel_hi:[1,1,0]
	s_waitcnt lgkmcnt(0)
	v_pk_fma_f32 v[12:13], v[40:41], v[46:47], 0 op_sel_hi:[1,1,0]
	v_pk_fma_f32 v[16:17], v[42:43], v[48:49], 0 op_sel_hi:[1,1,0]
